# v9 + priority 3 during the K/V prefetch-load and K-fragment read burst at the top of each attention A/D tile, back to 1 before QK
# baseline (speedup 1.0000x reference)
.LBB0_66:
	s_setprio 3
	global_load_dwordx4 v[90:93], v180, s[62:63]
	global_load_dwordx4 v[94:97], v178, s[62:63]
	global_load_dwordx4 v[106:109], v176, s[62:63]
	global_load_dwordx4 v[102:105], v[172:173], off
	global_load_dwordx4 v[98:101], v[174:175], off
	s_and_b32 s9, 1, s14
	s_cselect_b32 s10, 0, 0x5600
	v_or_b32_e32 v34, s10, v197
	v_add_u32_e32 v129, v34, v198
	ds_read_b128 v[34:37], v129
	ds_read_b128 v[38:41], v129 offset:6656
	ds_read_b128 v[110:113], v129 offset:32
	ds_read_b128 v[114:117], v129 offset:6688
	s_setprio 1
	s_waitcnt vmcnt(10) lgkmcnt(3)
	v_mfma_f32_32x32x16_bf16 v[50:65], v[34:37], v[86:89], 0
	s_waitcnt lgkmcnt(2)
	v_mfma_f32_32x32x16_bf16 v[34:49], v[38:41], v[86:89], 0
	ds_read_b128 v[200:203], v129 offset:64
	ds_read_b128 v[232:235], v129 offset:6720
	s_waitcnt vmcnt(9) lgkmcnt(3)
	v_mfma_f32_32x32x16_bf16 v[50:65], v[110:113], v[82:85], v[50:65]
	s_waitcnt lgkmcnt(2)
	v_mfma_f32_32x32x16_bf16 v[34:49], v[114:117], v[82:85], v[34:49]
	ds_read_b128 v[110:113], v129 offset:96
	ds_read_b128 v[114:117], v129 offset:6752
	s_waitcnt vmcnt(8) lgkmcnt(3)
	v_mfma_f32_32x32x16_bf16 v[50:65], v[200:203], v[78:81], v[50:65]
	s_waitcnt lgkmcnt(2)
	v_mfma_f32_32x32x16_bf16 v[34:49], v[232:235], v[78:81], v[34:49]
	ds_read_b128 v[200:203], v129 offset:128
	ds_read_b128 v[232:235], v129 offset:6784
	s_waitcnt vmcnt(7) lgkmcnt(3)
	v_mfma_f32_32x32x16_bf16 v[50:65], v[110:113], v[74:77], v[50:65]
	s_waitcnt lgkmcnt(2)
	v_mfma_f32_32x32x16_bf16 v[34:49], v[114:117], v[74:77], v[34:49]
	ds_read_b128 v[110:113], v129 offset:160
	ds_read_b128 v[114:117], v129 offset:6816
	s_waitcnt vmcnt(6) lgkmcnt(3)
	v_mfma_f32_32x32x16_bf16 v[50:65], v[200:203], v[70:73], v[50:65]
	s_waitcnt lgkmcnt(2)
	v_mfma_f32_32x32x16_bf16 v[34:49], v[232:235], v[70:73], v[34:49]
	s_waitcnt vmcnt(5) lgkmcnt(1)
	v_mfma_f32_32x32x16_bf16 v[50:65], v[110:113], v[66:69], v[50:65]
	s_waitcnt lgkmcnt(0)
	v_mfma_f32_32x32x16_bf16 v[34:49], v[114:117], v[66:69], v[34:49]
	v_or_b32_e32 v110, s10, v118
	v_add_u32_e32 v114, v110, v199
	v_add_u32_e32 v153, 0x3000, v114
	v_add_u32_e32 v129, 0x4000, v114
	ds_read2_b64 v[110:113], v153 offset0:128 offset1:130
	ds_read2_b64 v[114:117], v129 offset0:160 offset1:162
	s_nop 2
	v_max3_f32 v155, v50, s55, v51
	v_max3_f32 v155, v155, v52, v53
	v_max3_f32 v155, v155, v54, v55
	v_max3_f32 v155, v155, v56, v57
	v_max3_f32 v155, v155, v58, v59
	v_max3_f32 v155, v155, v60, v61
	v_max3_f32 v155, v155, v62, v63
	v_max3_f32 v155, v155, v64, v65
	v_max3_f32 v155, v155, v34, v35
	v_max3_f32 v155, v155, v36, v37
	v_max3_f32 v155, v155, v38, v39
	v_max3_f32 v155, v155, v40, v41
	v_max3_f32 v155, v155, v42, v43
	v_max3_f32 v155, v155, v44, v45
	v_max3_f32 v155, v155, v46, v47
	v_max3_f32 v155, v155, v48, v49
	v_mov_b32_e32 v169, v155
	s_nop 1
	v_permlane32_swap_b32_e32 v155, v169
	v_max_f32_e32 v169, v169, v169
	v_max_f32_e32 v155, v155, v155
	v_max_f32_e32 v155, v155, v169
	v_mul_f32_e32 v155, 0x3e16c740, v155
	v_add_f32_e32 v169, 0x41000000, v188
	v_cmp_gt_f32_e32 vcc, v155, v169
	s_cbranch_vccz .LBB0_65
	v_max_f32_e32 v155, v155, v155
	v_max_f32_e32 v169, v188, v188
	v_max_f32_e32 v155, v169, v155
	v_sub_f32_e32 v169, v188, v155
	v_exp_f32_e32 v188, v169
	s_nop 0
	v_pk_mul_f32 v[32:33], v[32:33], v[188:189] op_sel_hi:[1,0]
	v_pk_mul_f32 v[30:31], v[30:31], v[188:189] op_sel_hi:[1,0]
	v_pk_mul_f32 v[28:29], v[28:29], v[188:189] op_sel_hi:[1,0]
	v_pk_mul_f32 v[26:27], v[26:27], v[188:189] op_sel_hi:[1,0]
	v_pk_mul_f32 v[24:25], v[24:25], v[188:189] op_sel_hi:[1,0]
	v_pk_mul_f32 v[22:23], v[22:23], v[188:189] op_sel_hi:[1,0]
	v_pk_mul_f32 v[20:21], v[20:21], v[188:189] op_sel_hi:[1,0]
	v_pk_mul_f32 v[18:19], v[18:19], v[188:189] op_sel_hi:[1,0]
	v_pk_mul_f32 v[16:17], v[16:17], v[188:189] op_sel_hi:[1,0]
	v_pk_mul_f32 v[14:15], v[14:15], v[188:189] op_sel_hi:[1,0]
	v_pk_mul_f32 v[12:13], v[12:13], v[188:189] op_sel_hi:[1,0]
	v_pk_mul_f32 v[10:11], v[10:11], v[188:189] op_sel_hi:[1,0]
	v_pk_mul_f32 v[8:9], v[8:9], v[188:189] op_sel_hi:[1,0]
	v_pk_mul_f32 v[6:7], v[6:7], v[188:189] op_sel_hi:[1,0]
	v_pk_mul_f32 v[4:5], v[4:5], v[188:189] op_sel_hi:[1,0]
	v_pk_mul_f32 v[2:3], v[2:3], v[188:189] op_sel_hi:[1,0]
	v_mul_f32_e32 v127, v127, v188
	v_mov_b32_e32 v188, v155
	s_branch .LBB0_65

.LBB0_867:
	s_setprio 3
	v_lshl_add_u64 v[2:3], v[156:157], 0, v[130:131]
	v_lshl_add_u64 v[6:7], v[158:159], 0, v[130:131]
	global_load_dwordx4 v[96:99], v[154:155], off
	global_load_dwordx4 v[10:13], v[152:153], off
	s_nop 0
	global_load_dwordx4 v[2:5], v[2:3], off
	s_nop 0
	global_load_dwordx4 v[6:9], v[6:7], off
	s_bitcmp1_b32 s7, 0
	s_cselect_b32 s0, 0x4600, 0
	v_or_b32_e32 v0, s0, v184
	v_add_u32_e32 v0, v0, v201
	ds_read_b128 v[48:51], v0
	ds_read_b128 v[52:55], v0 offset:4608
	ds_read_b128 v[100:103], v0 offset:32
	ds_read_b128 v[104:107], v0 offset:4640
	s_setprio 1
	s_waitcnt vmcnt(7) lgkmcnt(3)
	v_mfma_f32_32x32x16_bf16 v[64:79], v[48:51], v[92:95], 0
	s_waitcnt lgkmcnt(2)
	v_mfma_f32_32x32x16_bf16 v[48:63], v[52:55], v[92:95], 0
	ds_read_b128 v[162:165], v0 offset:64
	ds_read_b128 v[166:169], v0 offset:4672
	s_waitcnt vmcnt(6) lgkmcnt(3)
	v_mfma_f32_32x32x16_bf16 v[64:79], v[100:103], v[88:91], v[64:79]
	s_waitcnt lgkmcnt(2)
	v_mfma_f32_32x32x16_bf16 v[48:63], v[104:107], v[88:91], v[48:63]
	ds_read_b128 v[100:103], v0 offset:96
	ds_read_b128 v[104:107], v0 offset:4704
	s_waitcnt vmcnt(5) lgkmcnt(3)
	v_mfma_f32_32x32x16_bf16 v[64:79], v[162:165], v[84:87], v[64:79]
	s_waitcnt lgkmcnt(2)
	v_mfma_f32_32x32x16_bf16 v[48:63], v[166:169], v[84:87], v[48:63]
	s_waitcnt vmcnt(4) lgkmcnt(1)
	v_mfma_f32_32x32x16_bf16 v[64:79], v[100:103], v[80:83], v[64:79]
	s_waitcnt lgkmcnt(0)
	v_mfma_f32_32x32x16_bf16 v[48:63], v[104:107], v[80:83], v[48:63]
	v_or_b32_e32 v0, s0, v116
	v_add_u32_e32 v0, v0, v202
	v_add_u32_e32 v14, 0x2000, v0
	v_add_u32_e32 v0, 0x3000, v0
	ds_read2_b64 v[100:103], v14 offset0:128 offset1:130
	ds_read2_b64 v[104:107], v0 offset0:160 offset1:162
	s_nop 2
	v_max3_f32 v15, v64, s55, v65
	v_max3_f32 v15, v15, v66, v67
	v_max3_f32 v15, v15, v68, v69
	v_max3_f32 v15, v15, v70, v71
	v_max3_f32 v15, v15, v72, v73
	v_max3_f32 v15, v15, v74, v75
	v_max3_f32 v15, v15, v76, v77
	v_max3_f32 v15, v15, v78, v79
	v_max3_f32 v15, v15, v48, v49
	v_max3_f32 v15, v15, v50, v51
	v_max3_f32 v15, v15, v52, v53
	v_max3_f32 v15, v15, v54, v55
	v_max3_f32 v15, v15, v56, v57
	v_max3_f32 v15, v15, v58, v59
	v_max3_f32 v15, v15, v60, v61
	v_max3_f32 v15, v15, v62, v63
	v_mov_b32_e32 v143, v15
	s_nop 1
	v_permlane32_swap_b32_e32 v15, v143
	v_max_f32_e32 v143, v143, v143
	v_max_f32_e32 v15, v15, v15
	v_max_f32_e32 v15, v15, v143
	v_mul_f32_e32 v15, 0x3e38aa3b, v15
	v_add_f32_e32 v143, 0x41000000, v160
	v_cmp_gt_f32_e32 vcc, v15, v143
	s_cbranch_vccz .LBB0_866
	v_max_f32_e32 v15, v15, v15
	v_max_f32_e32 v143, v160, v160
	v_max_f32_e32 v15, v143, v15
	v_sub_f32_e32 v143, v160, v15
	v_exp_f32_e32 v160, v143
	s_nop 0
	v_pk_mul_f32 v[46:47], v[46:47], v[160:161] op_sel_hi:[1,0]
	v_pk_mul_f32 v[44:45], v[44:45], v[160:161] op_sel_hi:[1,0]
	v_pk_mul_f32 v[42:43], v[42:43], v[160:161] op_sel_hi:[1,0]
	v_pk_mul_f32 v[40:41], v[40:41], v[160:161] op_sel_hi:[1,0]
	v_pk_mul_f32 v[38:39], v[38:39], v[160:161] op_sel_hi:[1,0]
	v_pk_mul_f32 v[36:37], v[36:37], v[160:161] op_sel_hi:[1,0]
	v_pk_mul_f32 v[34:35], v[34:35], v[160:161] op_sel_hi:[1,0]
	v_pk_mul_f32 v[32:33], v[32:33], v[160:161] op_sel_hi:[1,0]
	v_pk_mul_f32 v[30:31], v[30:31], v[160:161] op_sel_hi:[1,0]
	v_pk_mul_f32 v[28:29], v[28:29], v[160:161] op_sel_hi:[1,0]
	v_pk_mul_f32 v[26:27], v[26:27], v[160:161] op_sel_hi:[1,0]
	v_pk_mul_f32 v[24:25], v[24:25], v[160:161] op_sel_hi:[1,0]
	v_pk_mul_f32 v[22:23], v[22:23], v[160:161] op_sel_hi:[1,0]
	v_pk_mul_f32 v[20:21], v[20:21], v[160:161] op_sel_hi:[1,0]
	v_pk_mul_f32 v[18:19], v[18:19], v[160:161] op_sel_hi:[1,0]
	v_pk_mul_f32 v[16:17], v[16:17], v[160:161] op_sel_hi:[1,0]
	v_mul_f32_e32 v141, v141, v160
	v_mov_b32_e32 v160, v15
	s_branch .LBB0_866
